# S8 plus SGU stage A: next chunk's stat and v loads issued before the current chunk's compute (register-renamed odd chunk), vmcnt re-derived
# speedup vs baseline: 1.0129x; 1.0000x over previous
; #define LAS __attribute__((address_space(3)))
; __device__ __forceinline__ unsigned cvt_pk_bf16(float lo, float hi) { unsigned r; asm volatile("v_cvt_pk_bf16_f32 %0, %1, %2" : "=v"(r) : "v"(lo), "v"(hi)); return r; }
; __device__ __forceinline__ float bf_lo(unsigned w) { return __uint_as_float(w << 16); }
; __device__ __forceinline__ float bf_hi(unsigned w) { return __uint_as_float(w & 0xffff0000u); }
; __device__ __forceinline__ void phase_sgu(const Params& p, int l, LAS unsigned char* lds, const bf16_t* proj, const float* sgst, const bf16_t* sgw, bf16_t* ymix, int G, int wv) {
;     ...
;         for (int i = 0; i < 4; ++i) { const int c = tid + 512 * i, s = c >> 4, dc = c & 15; const size_t tok = tok0 + s;
;             const f32x4* sp = (const f32x4*)(sgst + tok * 16); const f32x4 q0 = sp[0], q1 = sp[1], q2 = sp[2], q3 = sp[3];
;             const float s1 = (q0[0] + q0[2]) + (q1[0] + q1[2]) + (q2[0] + q2[2]) + (q3[0] + q3[2]), s2 = (q0[1] + q0[3]) + (q1[1] + q1[3]) + (q2[1] + q2[3]) + (q3[1] + q3[3]);
;             const float mean = s1 * (1.f / 512.f), var = s2 * (1.f / 512.f) - mean * mean, rstd = __builtin_amdgcn_rsqf(fmaxf(var, 0.f) + EPS);
;             const u32x4 x = *(const u32x4*)(proj + tok * NIN + PJ_V + head * 128 + dc * 8);
;             const float xv[8] = {bf_lo(x.x), bf_hi(x.x), bf_lo(x.y), bf_hi(x.y), bf_lo(x.z), bf_hi(x.z), bf_lo(x.w), bf_hi(x.w)};
;             const f32x4 g0 = *(const f32x4*)(ng + head * 128 + dc * 8), g1 = *(const f32x4*)(ng + head * 128 + dc * 8 + 4);
;             const f32x4 b0 = *(const f32x4*)(nb_ + head * 128 + dc * 8), b1 = *(const f32x4*)(nb_ + head * 128 + dc * 8 + 4);
; #pragma unroll
;             for (int j = 0; j < 8; ++j) { const float gj = j < 4 ? g0[j & 3] : g1[j & 3], bj = j < 4 ? b0[j & 3] : b1[j & 3];
;                 const float v = (xv[j] - mean) * rstd * gj + bj;
;                 *(LAS bf16_t*)(lds + (dc * 8 + j) * SG_ROW + s * 2) = (bf16_t)(cvt_pk_bf16(v, 0.f) & 0xffffu); } }
.LBB0_393:
	s_and_b32 s8, s27, 0xffffff80
	v_add_u32_e32 v74, s8, v91
	v_ashrrev_i32_e32 v75, 31, v74
	v_lshlrev_b64 v[4:5], 6, v[74:75]
	v_lshl_add_u64 v[16:17], s[12:13], 0, v[4:5]
	global_load_dwordx4 v[4:7], v[16:17], off offset:48
	global_load_dwordx4 v[8:11], v[16:17], off offset:32
	global_load_dwordx4 v[12:15], v[16:17], off offset:16
	s_nop 0
	global_load_dwordx4 v[16:19], v[16:17], off
	s_and_b32 s63, s0, 0x180
	s_lshl_b32 s36, s63, 2
	v_lshl_add_u64 v[0:1], v[62:63], 0, s[36:37]
	v_lshl_add_u64 v[2:3], v[64:65], 0, s[36:37]
	v_mad_i64_i32 v[78:79], s[10:11], v74, s59, v[68:69]
	s_lshl_b32 s36, s63, 1
	v_lshl_add_u64 v[20:21], v[78:79], 0, s[36:37]
	v_lshl_add_u64 v[20:21], v[20:21], 0, v[72:73]
	v_add_co_u32_e32 v20, vcc, s60, v20
	v_add_u32_e32 v76, s8, v92
	s_nop 0
	v_addc_co_u32_e32 v21, vcc, 0, v21, vcc
	global_load_dwordx4 v[20:23], v[20:21], off offset:3072
	s_nop 0
	global_load_dwordx4 v[24:27], v[2:3], off
	global_load_dwordx4 v[28:31], v[0:1], off
	global_load_dwordx4 v[32:35], v[0:1], off offset:16
	global_load_dwordx4 v[36:39], v[2:3], off offset:16
	v_ashrrev_i32_e32 v77, 31, v76
	v_lshlrev_b64 v[40:41], 6, v[76:77]
	v_lshl_add_u64 v[40:41], s[12:13], 0, v[40:41]
	v_mad_i64_i32 v[82:83], s[10:11], v76, s59, v[68:69]
	v_lshl_add_u64 v[42:43], v[82:83], 0, s[36:37]
	v_add_u32_e32 v80, s8, v93
	v_ashrrev_i32_e32 v81, 31, v80
	v_mad_i64_i32 v[86:87], s[10:11], v80, s59, v[68:69]
	v_add_u32_e32 v84, s8, v94
	v_ashrrev_i32_e32 v85, 31, v84
	v_mad_i64_i32 v[88:89], s[8:9], v84, s59, v[68:69]
	global_load_dwordx4 v[114:117], v[40:41], off offset:16
	global_load_dwordx4 v[118:121], v[40:41], off
	global_load_dwordx4 v[122:125], v[40:41], off offset:48
	global_load_dwordx4 v[126:129], v[40:41], off offset:32
	v_lshl_add_u64 v[130:131], v[42:43], 0, v[72:73]
	v_add_co_u32_e32 v130, vcc, s60, v130
	s_nop 1
	v_addc_co_u32_e32 v131, vcc, 0, v131, vcc
	global_load_dwordx4 v[130:133], v[130:131], off offset:3072
	s_waitcnt vmcnt(13)
	v_add_f32_e32 v4, v4, v6
	s_waitcnt vmcnt(12)
	v_add_f32_e32 v8, v8, v10
	s_waitcnt vmcnt(11)
	v_add_f32_e32 v12, v12, v14
	s_waitcnt vmcnt(10)
	v_add_f32_e32 v16, v16, v18
	v_add_f32_e32 v6, v17, v19
	v_add_f32_e32 v10, v13, v15
	v_add_f32_e32 v5, v5, v7
	v_add_f32_e32 v7, v16, v12
	v_add_f32_e32 v9, v9, v11
	v_add_f32_e32 v6, v6, v10
	v_add_f32_e32 v7, v7, v8
	v_add_f32_e32 v6, v6, v9
	v_add_f32_e32 v4, v7, v4
	v_add_f32_e32 v5, v6, v5
	v_mul_f32_e32 v6, 0x3b000000, v4
	v_mul_f32_e32 v6, v6, v6
	v_fma_f32 v5, v5, s58, -v6
	v_max_f32_e32 v5, 0, v5
	v_add_f32_e32 v5, 0x3727c5ac, v5
	v_rsq_f32_e32 v5, v5
	s_waitcnt vmcnt(9)
	v_lshlrev_b32_e32 v10, 16, v20
	v_and_b32_e32 v11, 0xffff0000, v20
	v_lshlrev_b32_e32 v12, 16, v21
	v_and_b32_e32 v13, 0xffff0000, v21
	v_lshlrev_b32_e32 v14, 16, v22
	v_and_b32_e32 v15, 0xffff0000, v22
	v_lshlrev_b32_e32 v16, 16, v23
	v_and_b32_e32 v17, 0xffff0000, v23
	v_fmac_f32_e32 v10, 0xbb000000, v4
	v_fmac_f32_e32 v11, 0xbb000000, v4
	v_fmac_f32_e32 v12, 0xbb000000, v4
	v_fmac_f32_e32 v13, 0xbb000000, v4
	v_fmac_f32_e32 v14, 0xbb000000, v4
	v_fmac_f32_e32 v15, 0xbb000000, v4
	v_fmac_f32_e32 v16, 0xbb000000, v4
	v_fmac_f32_e32 v17, 0xbb000000, v4
	v_mul_f32_e32 v4, v10, v5
	s_waitcnt vmcnt(7)
	v_fma_f32 v4, v28, v4, v24
	v_mul_f32_e32 v6, v11, v5
	v_cvt_pk_bf16_f32 v4, v4, v61
	v_mul_f32_e32 v7, v12, v5
	v_fma_f32 v6, v29, v6, v25
	ds_write_b16 v96, v4
	v_cvt_pk_bf16_f32 v4, v6, v61
	v_mul_f32_e32 v8, v13, v5
	v_fma_f32 v7, v30, v7, v26
	ds_write_b16 v96, v4 offset:272
	v_cvt_pk_bf16_f32 v4, v7, v61
	v_mul_f32_e32 v9, v14, v5
	v_fmac_f32_e32 v27, v31, v8
	ds_write_b16 v96, v4 offset:544
	v_cvt_pk_bf16_f32 v4, v27, v61
	v_mul_f32_e32 v10, v15, v5
	s_waitcnt vmcnt(5)
	v_fma_f32 v8, v32, v9, v36
	ds_write_b16 v96, v4 offset:816
	v_cvt_pk_bf16_f32 v4, v8, v61
	v_mul_f32_e32 v11, v16, v5
	v_fma_f32 v9, v33, v10, v37
	ds_write_b16 v96, v4 offset:1088
	v_cvt_pk_bf16_f32 v4, v9, v61
	v_mul_f32_e32 v5, v17, v5
	v_fma_f32 v10, v34, v11, v38
	ds_write_b16 v96, v4 offset:1360
	v_cvt_pk_bf16_f32 v4, v10, v61
	v_fmac_f32_e32 v39, v35, v5
	ds_write_b16 v96, v4 offset:1632
	v_cvt_pk_bf16_f32 v44, v39, v61
	v_lshlrev_b64 v[40:41], 6, v[80:81]
	s_nop 0
	global_load_dwordx4 v[134:137], v[2:3], off
	global_load_dwordx4 v[138:141], v[0:1], off
	global_load_dwordx4 v[142:145], v[0:1], off offset:16
	global_load_dwordx4 v[146:149], v[2:3], off offset:16
	ds_write_b16 v96, v44 offset:1904
	v_lshl_add_u64 v[40:41], s[12:13], 0, v[40:41]
	v_lshl_add_u64 v[42:43], v[86:87], 0, s[36:37]
	global_load_dwordx4 v[4:7], v[40:41], off offset:16
	global_load_dwordx4 v[8:11], v[40:41], off
	global_load_dwordx4 v[12:15], v[40:41], off offset:48
	global_load_dwordx4 v[16:19], v[40:41], off offset:32
	v_lshl_add_u64 v[20:21], v[42:43], 0, v[72:73]
	v_add_co_u32_e32 v20, vcc, s60, v20
	s_nop 1
	v_addc_co_u32_e32 v21, vcc, 0, v21, vcc
	global_load_dwordx4 v[20:23], v[20:21], off offset:3072
	s_waitcnt vmcnt(13)
	v_add_f32_e32 v114, v114, v116
	s_waitcnt vmcnt(12)
	v_add_f32_e32 v118, v118, v120
	v_add_f32_e32 v114, v118, v114
	s_waitcnt vmcnt(10)
	v_add_f32_e32 v116, v126, v128
	v_add_f32_e32 v120, v122, v124
	v_add_f32_e32 v119, v119, v121
	v_add_f32_e32 v115, v115, v117
	v_add_f32_e32 v114, v114, v116
	v_add_f32_e32 v117, v127, v129
	v_add_f32_e32 v115, v119, v115
	v_add_f32_e32 v114, v114, v120
	v_add_f32_e32 v121, v123, v125
	v_add_f32_e32 v115, v115, v117
	v_mul_f32_e32 v116, 0x3b000000, v114
	v_add_f32_e32 v115, v115, v121
	v_mul_f32_e32 v116, v116, v116
	v_fma_f32 v115, v115, s58, -v116
	v_max_f32_e32 v115, 0, v115
	v_add_f32_e32 v115, 0x3727c5ac, v115
	v_rsq_f32_e32 v115, v115
	s_waitcnt vmcnt(9)
; #define LAS __attribute__((address_space(3)))
; __device__ __forceinline__ unsigned cvt_pk_bf16(float lo, float hi) { unsigned r; asm volatile("v_cvt_pk_bf16_f32 %0, %1, %2" : "=v"(r) : "v"(lo), "v"(hi)); return r; }
; __device__ __forceinline__ float bf_lo(unsigned w) { return __uint_as_float(w << 16); }
; __device__ __forceinline__ float bf_hi(unsigned w) { return __uint_as_float(w & 0xffff0000u); }
; __device__ __forceinline__ void phase_sgu(const Params& p, int l, LAS unsigned char* lds, const bf16_t* proj, const float* sgst, const bf16_t* sgw, bf16_t* ymix, int G, int wv) {
;     ...
;         for (int i = 0; i < 4; ++i) { const int c = tid + 512 * i, s = c >> 4, dc = c & 15; const size_t tok = tok0 + s;
;             const f32x4* sp = (const f32x4*)(sgst + tok * 16); const f32x4 q0 = sp[0], q1 = sp[1], q2 = sp[2], q3 = sp[3];
;             const float s1 = (q0[0] + q0[2]) + (q1[0] + q1[2]) + (q2[0] + q2[2]) + (q3[0] + q3[2]), s2 = (q0[1] + q0[3]) + (q1[1] + q1[3]) + (q2[1] + q2[3]) + (q3[1] + q3[3]);
;             const float mean = s1 * (1.f / 512.f), var = s2 * (1.f / 512.f) - mean * mean, rstd = __builtin_amdgcn_rsqf(fmaxf(var, 0.f) + EPS);
;             const u32x4 x = *(const u32x4*)(proj + tok * NIN + PJ_V + head * 128 + dc * 8);
;             const float xv[8] = {bf_lo(x.x), bf_hi(x.x), bf_lo(x.y), bf_hi(x.y), bf_lo(x.z), bf_hi(x.z), bf_lo(x.w), bf_hi(x.w)};
;             const f32x4 g0 = *(const f32x4*)(ng + head * 128 + dc * 8), g1 = *(const f32x4*)(ng + head * 128 + dc * 8 + 4);
;             const f32x4 b0 = *(const f32x4*)(nb_ + head * 128 + dc * 8), b1 = *(const f32x4*)(nb_ + head * 128 + dc * 8 + 4);
; #pragma unroll
;             for (int j = 0; j < 8; ++j) { const float gj = j < 4 ? g0[j & 3] : g1[j & 3], bj = j < 4 ? b0[j & 3] : b1[j & 3];
;                 const float v = (xv[j] - mean) * rstd * gj + bj;
;                 *(LAS bf16_t*)(lds + (dc * 8 + j) * SG_ROW + s * 2) = (bf16_t)(cvt_pk_bf16(v, 0.f) & 0xffffu); } }
	v_lshlrev_b32_e32 v122, 16, v130
	v_and_b32_e32 v123, 0xffff0000, v130
	v_lshlrev_b32_e32 v124, 16, v131
	v_and_b32_e32 v125, 0xffff0000, v131
	v_lshlrev_b32_e32 v126, 16, v132
	v_and_b32_e32 v127, 0xffff0000, v132
	v_lshlrev_b32_e32 v128, 16, v133
	v_and_b32_e32 v129, 0xffff0000, v133
	v_fmac_f32_e32 v122, 0xbb000000, v114
	v_fmac_f32_e32 v123, 0xbb000000, v114
	v_fmac_f32_e32 v124, 0xbb000000, v114
	v_fmac_f32_e32 v125, 0xbb000000, v114
	v_fmac_f32_e32 v126, 0xbb000000, v114
	v_fmac_f32_e32 v127, 0xbb000000, v114
	v_fmac_f32_e32 v128, 0xbb000000, v114
	v_fmac_f32_e32 v129, 0xbb000000, v114
	v_mul_f32_e32 v114, v122, v115
	s_waitcnt vmcnt(7)
	v_fma_f32 v114, v138, v114, v134
	v_mul_f32_e32 v116, v123, v115
	v_cvt_pk_bf16_f32 v114, v114, v61
	v_mul_f32_e32 v117, v124, v115
	v_fma_f32 v116, v139, v116, v135
	ds_write_b16 v97, v114
	v_cvt_pk_bf16_f32 v114, v116, v61
	v_mul_f32_e32 v118, v125, v115
	v_fma_f32 v117, v140, v117, v136
	ds_write_b16 v97, v114 offset:272
	v_cvt_pk_bf16_f32 v114, v117, v61
	v_mul_f32_e32 v119, v126, v115
	v_fmac_f32_e32 v137, v141, v118
	ds_write_b16 v97, v114 offset:544
	v_cvt_pk_bf16_f32 v114, v137, v61
	v_mul_f32_e32 v120, v127, v115
	s_waitcnt vmcnt(5)
	v_fma_f32 v118, v142, v119, v146
	ds_write_b16 v97, v114 offset:816
	v_cvt_pk_bf16_f32 v114, v118, v61
	v_mul_f32_e32 v121, v128, v115
	v_fma_f32 v119, v143, v120, v147
	ds_write_b16 v97, v114 offset:1088
	v_cvt_pk_bf16_f32 v114, v119, v61
	v_mul_f32_e32 v115, v129, v115
	v_fma_f32 v120, v144, v121, v148
	ds_write_b16 v97, v114 offset:1360
	v_cvt_pk_bf16_f32 v114, v120, v61
	v_fmac_f32_e32 v149, v145, v115
	ds_write_b16 v97, v114 offset:1632
	v_cvt_pk_bf16_f32 v154, v149, v61
	v_lshlrev_b64 v[40:41], 6, v[84:85]
	s_nop 0
	global_load_dwordx4 v[24:27], v[2:3], off
	global_load_dwordx4 v[28:31], v[0:1], off
	global_load_dwordx4 v[32:35], v[0:1], off offset:16
	global_load_dwordx4 v[36:39], v[2:3], off offset:16
	ds_write_b16 v97, v154 offset:1904
	v_lshl_add_u64 v[40:41], s[12:13], 0, v[40:41]
	v_lshl_add_u64 v[42:43], v[88:89], 0, s[36:37]
	s_waitcnt vmcnt(8)
	v_add_f32_e32 v4, v4, v6
	s_waitcnt vmcnt(7)
	v_add_f32_e32 v8, v8, v10
	v_add_f32_e32 v4, v8, v4
	s_waitcnt vmcnt(5)
	v_add_f32_e32 v6, v16, v18
	v_add_f32_e32 v10, v12, v14
	v_add_f32_e32 v9, v9, v11
	v_add_f32_e32 v5, v5, v7
	v_add_f32_e32 v4, v4, v6
	v_add_f32_e32 v7, v17, v19
	v_add_f32_e32 v5, v9, v5
	v_add_f32_e32 v4, v4, v10
	v_add_f32_e32 v11, v13, v15
	v_add_f32_e32 v5, v5, v7
	v_mul_f32_e32 v6, 0x3b000000, v4
	v_add_f32_e32 v5, v5, v11
	v_mul_f32_e32 v6, v6, v6
	v_fma_f32 v5, v5, s58, -v6
	v_max_f32_e32 v5, 0, v5
	v_add_f32_e32 v5, 0x3727c5ac, v5
	v_rsq_f32_e32 v5, v5
	s_waitcnt vmcnt(4)
	v_lshlrev_b32_e32 v12, 16, v20
	v_and_b32_e32 v13, 0xffff0000, v20
	v_lshlrev_b32_e32 v14, 16, v21
	v_and_b32_e32 v15, 0xffff0000, v21
	v_lshlrev_b32_e32 v16, 16, v22
	v_and_b32_e32 v17, 0xffff0000, v22
	v_lshlrev_b32_e32 v18, 16, v23
	v_and_b32_e32 v19, 0xffff0000, v23
	v_fmac_f32_e32 v12, 0xbb000000, v4
	v_fmac_f32_e32 v13, 0xbb000000, v4
	v_fmac_f32_e32 v14, 0xbb000000, v4
	v_fmac_f32_e32 v15, 0xbb000000, v4
	v_fmac_f32_e32 v16, 0xbb000000, v4
	v_fmac_f32_e32 v17, 0xbb000000, v4
	v_fmac_f32_e32 v18, 0xbb000000, v4
	v_fmac_f32_e32 v19, 0xbb000000, v4
	v_mul_f32_e32 v4, v12, v5
	s_waitcnt vmcnt(2)
	v_fma_f32 v4, v28, v4, v24
	v_mul_f32_e32 v6, v13, v5
	v_cvt_pk_bf16_f32 v4, v4, v61
	v_mul_f32_e32 v7, v14, v5
	v_fma_f32 v6, v29, v6, v25
	ds_write_b16 v98, v4
	v_cvt_pk_bf16_f32 v4, v6, v61
	v_mul_f32_e32 v8, v15, v5
	v_fma_f32 v7, v30, v7, v26
	ds_write_b16 v98, v4 offset:272
	v_cvt_pk_bf16_f32 v4, v7, v61
	v_mul_f32_e32 v9, v16, v5
	v_fmac_f32_e32 v27, v31, v8
	ds_write_b16 v98, v4 offset:544
	v_cvt_pk_bf16_f32 v4, v27, v61
	v_mul_f32_e32 v10, v17, v5
	s_waitcnt vmcnt(0)
; #define LAS __attribute__((address_space(3)))
; __device__ __forceinline__ unsigned cvt_pk_bf16(float lo, float hi) { unsigned r; asm volatile("v_cvt_pk_bf16_f32 %0, %1, %2" : "=v"(r) : "v"(lo), "v"(hi)); return r; }
; __device__ __forceinline__ float bf_lo(unsigned w) { return __uint_as_float(w << 16); }
; __device__ __forceinline__ float bf_hi(unsigned w) { return __uint_as_float(w & 0xffff0000u); }
; __device__ __forceinline__ void phase_sgu(const Params& p, int l, LAS unsigned char* lds, const bf16_t* proj, const float* sgst, const bf16_t* sgw, bf16_t* ymix, int G, int wv) {
;     ...
;         for (int i = 0; i < 4; ++i) { const int c = tid + 512 * i, s = c >> 4, dc = c & 15; const size_t tok = tok0 + s;
;             const f32x4* sp = (const f32x4*)(sgst + tok * 16); const f32x4 q0 = sp[0], q1 = sp[1], q2 = sp[2], q3 = sp[3];
;             const float s1 = (q0[0] + q0[2]) + (q1[0] + q1[2]) + (q2[0] + q2[2]) + (q3[0] + q3[2]), s2 = (q0[1] + q0[3]) + (q1[1] + q1[3]) + (q2[1] + q2[3]) + (q3[1] + q3[3]);
;             const float mean = s1 * (1.f / 512.f), var = s2 * (1.f / 512.f) - mean * mean, rstd = __builtin_amdgcn_rsqf(fmaxf(var, 0.f) + EPS);
;             const u32x4 x = *(const u32x4*)(proj + tok * NIN + PJ_V + head * 128 + dc * 8);
;             const float xv[8] = {bf_lo(x.x), bf_hi(x.x), bf_lo(x.y), bf_hi(x.y), bf_lo(x.z), bf_hi(x.z), bf_lo(x.w), bf_hi(x.w)};
;             const f32x4 g0 = *(const f32x4*)(ng + head * 128 + dc * 8), g1 = *(const f32x4*)(ng + head * 128 + dc * 8 + 4);
;             const f32x4 b0 = *(const f32x4*)(nb_ + head * 128 + dc * 8), b1 = *(const f32x4*)(nb_ + head * 128 + dc * 8 + 4);
; #pragma unroll
;             for (int j = 0; j < 8; ++j) { const float gj = j < 4 ? g0[j & 3] : g1[j & 3], bj = j < 4 ? b0[j & 3] : b1[j & 3];
;                 const float v = (xv[j] - mean) * rstd * gj + bj;
;                 *(LAS bf16_t*)(lds + (dc * 8 + j) * SG_ROW + s * 2) = (bf16_t)(cvt_pk_bf16(v, 0.f) & 0xffffu); } }
;         const int tb = wave & 3, dh = wave >> 2;
;         const bf16_t* wrow = sgw + ((size_t)((l * 4 + head) * 128) + tb * 32 + l32) * 128 + 8 * hi;
;         bf16x8 af[8];
; #pragma unroll
;         for (int ks = 0; ks < 8; ++ks) { af[ks] = (bf16x8){0, 0, 0, 0, 0, 0, 0, 0}; if (ks < 2 * tb + 2) af[ks] = *(const bf16x8*)(wrow + 16 * ks); }
	v_fma_f32 v8, v32, v9, v36
	ds_write_b16 v98, v4 offset:816
	v_cvt_pk_bf16_f32 v4, v8, v61
	v_mul_f32_e32 v11, v18, v5
	v_fma_f32 v9, v33, v10, v37
	ds_write_b16 v98, v4 offset:1088
	v_cvt_pk_bf16_f32 v4, v9, v61
	v_mul_f32_e32 v5, v19, v5
	v_fma_f32 v10, v34, v11, v38
	ds_write_b16 v98, v4 offset:1360
	v_cvt_pk_bf16_f32 v4, v10, v61
	v_fmac_f32_e32 v39, v35, v5
	ds_write_b16 v98, v4 offset:1632
	v_cvt_pk_bf16_f32 v44, v39, v61
	global_load_dwordx4 v[4:7], v[40:41], off offset:16
	global_load_dwordx4 v[8:11], v[40:41], off
	global_load_dwordx4 v[12:15], v[40:41], off offset:48
	global_load_dwordx4 v[16:19], v[40:41], off offset:32
	v_lshl_add_u64 v[20:21], v[42:43], 0, v[72:73]
	v_add_co_u32_e32 v20, vcc, s60, v20
	s_waitcnt vmcnt(3)
	v_add_f32_e32 v5, v5, v7
	v_addc_co_u32_e32 v21, vcc, 0, v21, vcc
	global_load_dwordx4 v[20:23], v[20:21], off offset:3072
	s_nop 0
	global_load_dwordx4 v[24:27], v[2:3], off
	global_load_dwordx4 v[28:31], v[0:1], off
	global_load_dwordx4 v[32:35], v[0:1], off offset:16
	global_load_dwordx4 v[36:39], v[2:3], off offset:16
	s_waitcnt vmcnt(7)
	v_add_f32_e32 v2, v8, v10
	v_add_f32_e32 v3, v4, v6
	s_waitcnt vmcnt(5)
	v_add_f32_e32 v4, v16, v18
	v_add_f32_e32 v2, v2, v3
	v_add_f32_e32 v6, v12, v14
	v_add_f32_e32 v8, v9, v11
	v_add_f32_e32 v2, v2, v4
	v_add_f32_e32 v7, v17, v19
	v_add_f32_e32 v3, v8, v5
	v_add_f32_e32 v2, v2, v6
	v_add_f32_e32 v9, v13, v15
	v_add_f32_e32 v3, v3, v7
	v_mul_f32_e32 v4, 0x3b000000, v2
	v_add_f32_e32 v3, v3, v9
	v_mul_f32_e32 v4, v4, v4
	v_fma_f32 v3, v3, s58, -v4
	v_max_f32_e32 v3, 0, v3
	v_add_f32_e32 v3, 0x3727c5ac, v3
	v_rsq_f32_e32 v3, v3
	ds_write_b16 v98, v44 offset:1904
	v_or_b32_e32 v0, s63, v90
	v_lshlrev_b32_e32 v60, 8, v0
	v_lshl_add_u64 v[0:1], v[66:67], 0, v[60:61]
	s_and_b64 vcc, exec, s[6:7]
	s_waitcnt vmcnt(4)
	v_lshlrev_b32_e32 v10, 16, v20
	v_and_b32_e32 v11, 0xffff0000, v20
	v_lshlrev_b32_e32 v12, 16, v21
	v_and_b32_e32 v13, 0xffff0000, v21
	v_lshlrev_b32_e32 v14, 16, v22
	v_and_b32_e32 v15, 0xffff0000, v22
	v_lshlrev_b32_e32 v16, 16, v23
	v_and_b32_e32 v17, 0xffff0000, v23
	v_fmac_f32_e32 v10, 0xbb000000, v2
	v_fmac_f32_e32 v11, 0xbb000000, v2
	v_fmac_f32_e32 v12, 0xbb000000, v2
	v_fmac_f32_e32 v13, 0xbb000000, v2
	v_fmac_f32_e32 v14, 0xbb000000, v2
	v_fmac_f32_e32 v15, 0xbb000000, v2
	v_fmac_f32_e32 v16, 0xbb000000, v2
	v_fmac_f32_e32 v17, 0xbb000000, v2
	v_mul_f32_e32 v2, v10, v3
	s_waitcnt vmcnt(2)
	v_fma_f32 v2, v28, v2, v24
	v_mul_f32_e32 v4, v11, v3
	v_cvt_pk_bf16_f32 v2, v2, v61
	v_mul_f32_e32 v5, v12, v3
	v_fma_f32 v4, v29, v4, v25
	ds_write_b16 v99, v2
	v_cvt_pk_bf16_f32 v2, v4, v61
	v_mul_f32_e32 v6, v13, v3
	v_fma_f32 v5, v30, v5, v26
	ds_write_b16 v99, v2 offset:272
	v_cvt_pk_bf16_f32 v2, v5, v61
	v_mul_f32_e32 v7, v14, v3
	v_fmac_f32_e32 v27, v31, v6
	ds_write_b16 v99, v2 offset:544
	v_cvt_pk_bf16_f32 v2, v27, v61
	v_mul_f32_e32 v8, v15, v3
	s_waitcnt vmcnt(0)
	v_fma_f32 v6, v32, v7, v36
	ds_write_b16 v99, v2 offset:816
	v_cvt_pk_bf16_f32 v2, v6, v61
	v_mul_f32_e32 v9, v16, v3
	v_fma_f32 v7, v33, v8, v37
	ds_write_b16 v99, v2 offset:1088
	v_cvt_pk_bf16_f32 v2, v7, v61
	v_mul_f32_e32 v3, v17, v3
	v_fma_f32 v8, v34, v9, v38
	ds_write_b16 v99, v2 offset:1360
	v_cvt_pk_bf16_f32 v2, v8, v61
	v_fmac_f32_e32 v39, v35, v3
	ds_write_b16 v99, v2 offset:1632
	v_cvt_pk_bf16_f32 v2, v39, v61
	global_load_dwordx4 v[16:19], v[0:1], off
	global_load_dwordx4 v[40:43], v[0:1], off offset:32
	ds_write_b16 v99, v2 offset:1904
	s_cbranch_vccnz .LBB0_400
	global_load_dwordx4 v[32:35], v[0:1], off offset:64
	s_and_b64 vcc, exec, s[6:7]
	s_cbranch_vccnz .LBB0_401

; #define LAS __attribute__((address_space(3)))
; __device__ __forceinline__ unsigned cvt_pk_bf16(float lo, float hi) { unsigned r; asm volatile("v_cvt_pk_bf16_f32 %0, %1, %2" : "=v"(r) : "v"(lo), "v"(hi)); return r; }
; __device__ __forceinline__ float bf_lo(unsigned w) { return __uint_as_float(w << 16); }
; __device__ __forceinline__ float bf_hi(unsigned w) { return __uint_as_float(w & 0xffff0000u); }
; __device__ __forceinline__ void phase_sgu(const Params& p, int l, LAS unsigned char* lds, const bf16_t* proj, const float* sgst, const bf16_t* sgw, bf16_t* ymix, int G, int wv) {
;     ...
;         for (int i = 0; i < 4; ++i) { const int c = tid + 512 * i, s = c >> 4, dc = c & 15; const size_t tok = tok0 + s;
;             const f32x4* sp = (const f32x4*)(sgst + tok * 16); const f32x4 q0 = sp[0], q1 = sp[1], q2 = sp[2], q3 = sp[3];
;             const float s1 = (q0[0] + q0[2]) + (q1[0] + q1[2]) + (q2[0] + q2[2]) + (q3[0] + q3[2]), s2 = (q0[1] + q0[3]) + (q1[1] + q1[3]) + (q2[1] + q2[3]) + (q3[1] + q3[3]);
;             const float mean = s1 * (1.f / 512.f), var = s2 * (1.f / 512.f) - mean * mean, rstd = __builtin_amdgcn_rsqf(fmaxf(var, 0.f) + EPS);
;             const u32x4 x = *(const u32x4*)(proj + tok * NIN + PJ_V + head * 128 + dc * 8);
;             const float xv[8] = {bf_lo(x.x), bf_hi(x.x), bf_lo(x.y), bf_hi(x.y), bf_lo(x.z), bf_hi(x.z), bf_lo(x.w), bf_hi(x.w)};
;             const f32x4 g0 = *(const f32x4*)(ng + head * 128 + dc * 8), g1 = *(const f32x4*)(ng + head * 128 + dc * 8 + 4);
;             const f32x4 b0 = *(const f32x4*)(nb_ + head * 128 + dc * 8), b1 = *(const f32x4*)(nb_ + head * 128 + dc * 8 + 4);
; #pragma unroll
;             for (int j = 0; j < 8; ++j) { const float gj = j < 4 ? g0[j & 3] : g1[j & 3], bj = j < 4 ? b0[j & 3] : b1[j & 3];
;                 const float v = (xv[j] - mean) * rstd * gj + bj;
;                 *(LAS bf16_t*)(lds + (dc * 8 + j) * SG_ROW + s * 2) = (bf16_t)(cvt_pk_bf16(v, 0.f) & 0xffffu); } }
.LBB0_958:
	s_and_b32 s8, s42, 0xffffff80
	v_add_u32_e32 v74, s8, v91
	v_ashrrev_i32_e32 v75, 31, v74
	v_lshlrev_b64 v[4:5], 6, v[74:75]
	v_lshl_add_u64 v[16:17], s[60:61], 0, v[4:5]
	global_load_dwordx4 v[4:7], v[16:17], off offset:48
	global_load_dwordx4 v[8:11], v[16:17], off offset:32
	global_load_dwordx4 v[12:15], v[16:17], off offset:16
	s_nop 0
	global_load_dwordx4 v[16:19], v[16:17], off
	s_and_b32 s66, s27, 0x180
	s_lshl_b32 s62, s66, 2
	v_lshl_add_u64 v[0:1], v[62:63], 0, s[62:63]
	v_lshl_add_u64 v[2:3], v[64:65], 0, s[62:63]
	v_mad_i64_i32 v[78:79], s[14:15], v74, s44, v[68:69]
	s_lshl_b32 s62, s66, 1
	v_lshl_add_u64 v[20:21], v[78:79], 0, s[62:63]
	v_lshl_add_u64 v[20:21], v[20:21], 0, v[72:73]
	v_add_co_u32_e32 v20, vcc, s45, v20
	v_add_u32_e32 v76, s8, v92
	s_nop 0
	v_addc_co_u32_e32 v21, vcc, 0, v21, vcc
	global_load_dwordx4 v[20:23], v[20:21], off offset:3072
	s_nop 0
	global_load_dwordx4 v[24:27], v[2:3], off offset:2048
	global_load_dwordx4 v[28:31], v[0:1], off offset:2048
	global_load_dwordx4 v[32:35], v[0:1], off offset:2064
	global_load_dwordx4 v[36:39], v[2:3], off offset:2064
	v_ashrrev_i32_e32 v77, 31, v76
	v_lshlrev_b64 v[40:41], 6, v[76:77]
	v_lshl_add_u64 v[40:41], s[60:61], 0, v[40:41]
	v_mad_i64_i32 v[82:83], s[14:15], v76, s44, v[68:69]
	v_lshl_add_u64 v[42:43], v[82:83], 0, s[62:63]
	v_add_u32_e32 v80, s8, v93
	v_ashrrev_i32_e32 v81, 31, v80
	v_mad_i64_i32 v[86:87], s[14:15], v80, s44, v[68:69]
	v_add_u32_e32 v84, s8, v94
	v_ashrrev_i32_e32 v85, 31, v84
	v_mad_i64_i32 v[88:89], s[8:9], v84, s44, v[68:69]
	global_load_dwordx4 v[114:117], v[40:41], off offset:16
	global_load_dwordx4 v[118:121], v[40:41], off
	global_load_dwordx4 v[122:125], v[40:41], off offset:48
	global_load_dwordx4 v[126:129], v[40:41], off offset:32
	v_lshl_add_u64 v[130:131], v[42:43], 0, v[72:73]
	v_add_co_u32_e32 v130, vcc, s45, v130
	s_nop 1
	v_addc_co_u32_e32 v131, vcc, 0, v131, vcc
	global_load_dwordx4 v[130:133], v[130:131], off offset:3072
	s_waitcnt vmcnt(13)
	v_add_f32_e32 v4, v4, v6
	s_waitcnt vmcnt(12)
	v_add_f32_e32 v8, v8, v10
	s_waitcnt vmcnt(11)
	v_add_f32_e32 v12, v12, v14
	s_waitcnt vmcnt(10)
	v_add_f32_e32 v16, v16, v18
	v_add_f32_e32 v6, v17, v19
	v_add_f32_e32 v10, v13, v15
	v_add_f32_e32 v5, v5, v7
	v_add_f32_e32 v7, v16, v12
	v_add_f32_e32 v9, v9, v11
	v_add_f32_e32 v6, v6, v10
	v_add_f32_e32 v7, v7, v8
	v_add_f32_e32 v6, v6, v9
	v_add_f32_e32 v4, v7, v4
	v_add_f32_e32 v5, v6, v5
	v_mul_f32_e32 v6, 0x3b000000, v4
	v_mul_f32_e32 v6, v6, v6
	v_fma_f32 v5, v5, s43, -v6
	v_max_f32_e32 v5, 0, v5
	v_add_f32_e32 v5, 0x3727c5ac, v5
	v_rsq_f32_e32 v5, v5
	s_waitcnt vmcnt(9)
	v_lshlrev_b32_e32 v10, 16, v20
	v_and_b32_e32 v11, 0xffff0000, v20
	v_lshlrev_b32_e32 v12, 16, v21
	v_and_b32_e32 v13, 0xffff0000, v21
	v_lshlrev_b32_e32 v14, 16, v22
	v_and_b32_e32 v15, 0xffff0000, v22
	v_lshlrev_b32_e32 v16, 16, v23
	v_and_b32_e32 v17, 0xffff0000, v23
	v_fmac_f32_e32 v10, 0xbb000000, v4
	v_fmac_f32_e32 v11, 0xbb000000, v4
	v_fmac_f32_e32 v12, 0xbb000000, v4
	v_fmac_f32_e32 v13, 0xbb000000, v4
	v_fmac_f32_e32 v14, 0xbb000000, v4
	v_fmac_f32_e32 v15, 0xbb000000, v4
	v_fmac_f32_e32 v16, 0xbb000000, v4
	v_fmac_f32_e32 v17, 0xbb000000, v4
	v_mul_f32_e32 v4, v10, v5
	s_waitcnt vmcnt(7)
	v_fma_f32 v4, v28, v4, v24
	v_mul_f32_e32 v6, v11, v5
	v_cvt_pk_bf16_f32 v4, v4, v61
	v_mul_f32_e32 v7, v12, v5
	v_fma_f32 v6, v29, v6, v25
	ds_write_b16 v96, v4
	v_cvt_pk_bf16_f32 v4, v6, v61
	v_mul_f32_e32 v8, v13, v5
	v_fma_f32 v7, v30, v7, v26
	ds_write_b16 v96, v4 offset:272
	v_cvt_pk_bf16_f32 v4, v7, v61
	v_mul_f32_e32 v9, v14, v5
	v_fmac_f32_e32 v27, v31, v8
	ds_write_b16 v96, v4 offset:544
	v_cvt_pk_bf16_f32 v4, v27, v61
	v_mul_f32_e32 v10, v15, v5
	s_waitcnt vmcnt(5)
	v_fma_f32 v8, v32, v9, v36
	ds_write_b16 v96, v4 offset:816
	v_cvt_pk_bf16_f32 v4, v8, v61
	v_mul_f32_e32 v11, v16, v5
	v_fma_f32 v9, v33, v10, v37
	ds_write_b16 v96, v4 offset:1088
	v_cvt_pk_bf16_f32 v4, v9, v61
	v_mul_f32_e32 v5, v17, v5
	v_fma_f32 v10, v34, v11, v38
	ds_write_b16 v96, v4 offset:1360
	v_cvt_pk_bf16_f32 v4, v10, v61
	v_fmac_f32_e32 v39, v35, v5
	ds_write_b16 v96, v4 offset:1632
	v_cvt_pk_bf16_f32 v44, v39, v61
	v_lshlrev_b64 v[40:41], 6, v[80:81]
	s_nop 0
	global_load_dwordx4 v[134:137], v[2:3], off offset:2048
	global_load_dwordx4 v[138:141], v[0:1], off offset:2048
	global_load_dwordx4 v[142:145], v[0:1], off offset:2064
	global_load_dwordx4 v[146:149], v[2:3], off offset:2064
	ds_write_b16 v96, v44 offset:1904
	v_lshl_add_u64 v[40:41], s[60:61], 0, v[40:41]
	v_lshl_add_u64 v[42:43], v[86:87], 0, s[62:63]
	global_load_dwordx4 v[4:7], v[40:41], off offset:16
	global_load_dwordx4 v[8:11], v[40:41], off
	global_load_dwordx4 v[12:15], v[40:41], off offset:48
	global_load_dwordx4 v[16:19], v[40:41], off offset:32
	v_lshl_add_u64 v[20:21], v[42:43], 0, v[72:73]
	v_add_co_u32_e32 v20, vcc, s45, v20
	s_nop 1
	v_addc_co_u32_e32 v21, vcc, 0, v21, vcc
	global_load_dwordx4 v[20:23], v[20:21], off offset:3072
	s_waitcnt vmcnt(13)
	v_add_f32_e32 v114, v114, v116
	s_waitcnt vmcnt(12)
	v_add_f32_e32 v118, v118, v120
	v_add_f32_e32 v114, v118, v114
	s_waitcnt vmcnt(10)
	v_add_f32_e32 v116, v126, v128
	v_add_f32_e32 v120, v122, v124
	v_add_f32_e32 v119, v119, v121
	v_add_f32_e32 v115, v115, v117
	v_add_f32_e32 v114, v114, v116
	v_add_f32_e32 v117, v127, v129
	v_add_f32_e32 v115, v119, v115
	v_add_f32_e32 v114, v114, v120
	v_add_f32_e32 v121, v123, v125
	v_add_f32_e32 v115, v115, v117
	v_mul_f32_e32 v116, 0x3b000000, v114
	v_add_f32_e32 v115, v115, v121
	v_mul_f32_e32 v116, v116, v116
	v_fma_f32 v115, v115, s43, -v116
	v_max_f32_e32 v115, 0, v115
	v_add_f32_e32 v115, 0x3727c5ac, v115
	v_rsq_f32_e32 v115, v115
	s_waitcnt vmcnt(9)
; #define LAS __attribute__((address_space(3)))
; __device__ __forceinline__ unsigned cvt_pk_bf16(float lo, float hi) { unsigned r; asm volatile("v_cvt_pk_bf16_f32 %0, %1, %2" : "=v"(r) : "v"(lo), "v"(hi)); return r; }
; __device__ __forceinline__ float bf_lo(unsigned w) { return __uint_as_float(w << 16); }
; __device__ __forceinline__ float bf_hi(unsigned w) { return __uint_as_float(w & 0xffff0000u); }
; __device__ __forceinline__ void phase_sgu(const Params& p, int l, LAS unsigned char* lds, const bf16_t* proj, const float* sgst, const bf16_t* sgw, bf16_t* ymix, int G, int wv) {
;     ...
;         for (int i = 0; i < 4; ++i) { const int c = tid + 512 * i, s = c >> 4, dc = c & 15; const size_t tok = tok0 + s;
;             const f32x4* sp = (const f32x4*)(sgst + tok * 16); const f32x4 q0 = sp[0], q1 = sp[1], q2 = sp[2], q3 = sp[3];
;             const float s1 = (q0[0] + q0[2]) + (q1[0] + q1[2]) + (q2[0] + q2[2]) + (q3[0] + q3[2]), s2 = (q0[1] + q0[3]) + (q1[1] + q1[3]) + (q2[1] + q2[3]) + (q3[1] + q3[3]);
;             const float mean = s1 * (1.f / 512.f), var = s2 * (1.f / 512.f) - mean * mean, rstd = __builtin_amdgcn_rsqf(fmaxf(var, 0.f) + EPS);
;             const u32x4 x = *(const u32x4*)(proj + tok * NIN + PJ_V + head * 128 + dc * 8);
;             const float xv[8] = {bf_lo(x.x), bf_hi(x.x), bf_lo(x.y), bf_hi(x.y), bf_lo(x.z), bf_hi(x.z), bf_lo(x.w), bf_hi(x.w)};
;             const f32x4 g0 = *(const f32x4*)(ng + head * 128 + dc * 8), g1 = *(const f32x4*)(ng + head * 128 + dc * 8 + 4);
;             const f32x4 b0 = *(const f32x4*)(nb_ + head * 128 + dc * 8), b1 = *(const f32x4*)(nb_ + head * 128 + dc * 8 + 4);
; #pragma unroll
;             for (int j = 0; j < 8; ++j) { const float gj = j < 4 ? g0[j & 3] : g1[j & 3], bj = j < 4 ? b0[j & 3] : b1[j & 3];
;                 const float v = (xv[j] - mean) * rstd * gj + bj;
;                 *(LAS bf16_t*)(lds + (dc * 8 + j) * SG_ROW + s * 2) = (bf16_t)(cvt_pk_bf16(v, 0.f) & 0xffffu); } }
	v_lshlrev_b32_e32 v122, 16, v130
	v_and_b32_e32 v123, 0xffff0000, v130
	v_lshlrev_b32_e32 v124, 16, v131
	v_and_b32_e32 v125, 0xffff0000, v131
	v_lshlrev_b32_e32 v126, 16, v132
	v_and_b32_e32 v127, 0xffff0000, v132
	v_lshlrev_b32_e32 v128, 16, v133
	v_and_b32_e32 v129, 0xffff0000, v133
	v_fmac_f32_e32 v122, 0xbb000000, v114
	v_fmac_f32_e32 v123, 0xbb000000, v114
	v_fmac_f32_e32 v124, 0xbb000000, v114
	v_fmac_f32_e32 v125, 0xbb000000, v114
	v_fmac_f32_e32 v126, 0xbb000000, v114
	v_fmac_f32_e32 v127, 0xbb000000, v114
	v_fmac_f32_e32 v128, 0xbb000000, v114
	v_fmac_f32_e32 v129, 0xbb000000, v114
	v_mul_f32_e32 v114, v122, v115
	s_waitcnt vmcnt(7)
	v_fma_f32 v114, v138, v114, v134
	v_mul_f32_e32 v116, v123, v115
	v_cvt_pk_bf16_f32 v114, v114, v61
	v_mul_f32_e32 v117, v124, v115
	v_fma_f32 v116, v139, v116, v135
	ds_write_b16 v97, v114
	v_cvt_pk_bf16_f32 v114, v116, v61
	v_mul_f32_e32 v118, v125, v115
	v_fma_f32 v117, v140, v117, v136
	ds_write_b16 v97, v114 offset:272
	v_cvt_pk_bf16_f32 v114, v117, v61
	v_mul_f32_e32 v119, v126, v115
	v_fmac_f32_e32 v137, v141, v118
	ds_write_b16 v97, v114 offset:544
	v_cvt_pk_bf16_f32 v114, v137, v61
	v_mul_f32_e32 v120, v127, v115
	s_waitcnt vmcnt(5)
	v_fma_f32 v118, v142, v119, v146
	ds_write_b16 v97, v114 offset:816
	v_cvt_pk_bf16_f32 v114, v118, v61
	v_mul_f32_e32 v121, v128, v115
	v_fma_f32 v119, v143, v120, v147
	ds_write_b16 v97, v114 offset:1088
	v_cvt_pk_bf16_f32 v114, v119, v61
	v_mul_f32_e32 v115, v129, v115
	v_fma_f32 v120, v144, v121, v148
	ds_write_b16 v97, v114 offset:1360
	v_cvt_pk_bf16_f32 v114, v120, v61
	v_fmac_f32_e32 v149, v145, v115
	ds_write_b16 v97, v114 offset:1632
	v_cvt_pk_bf16_f32 v154, v149, v61
	v_lshlrev_b64 v[40:41], 6, v[84:85]
	s_nop 0
	global_load_dwordx4 v[24:27], v[2:3], off offset:2048
	global_load_dwordx4 v[28:31], v[0:1], off offset:2048
	global_load_dwordx4 v[32:35], v[0:1], off offset:2064
	global_load_dwordx4 v[36:39], v[2:3], off offset:2064
	ds_write_b16 v97, v154 offset:1904
	v_lshl_add_u64 v[40:41], s[60:61], 0, v[40:41]
	v_lshl_add_u64 v[42:43], v[88:89], 0, s[62:63]
	s_waitcnt vmcnt(8)
	v_add_f32_e32 v4, v4, v6
	s_waitcnt vmcnt(7)
	v_add_f32_e32 v8, v8, v10
	v_add_f32_e32 v4, v8, v4
	s_waitcnt vmcnt(5)
	v_add_f32_e32 v6, v16, v18
	v_add_f32_e32 v10, v12, v14
	v_add_f32_e32 v9, v9, v11
	v_add_f32_e32 v5, v5, v7
	v_add_f32_e32 v4, v4, v6
	v_add_f32_e32 v7, v17, v19
	v_add_f32_e32 v5, v9, v5
	v_add_f32_e32 v4, v4, v10
	v_add_f32_e32 v11, v13, v15
	v_add_f32_e32 v5, v5, v7
	v_mul_f32_e32 v6, 0x3b000000, v4
	v_add_f32_e32 v5, v5, v11
	v_mul_f32_e32 v6, v6, v6
	v_fma_f32 v5, v5, s43, -v6
	v_max_f32_e32 v5, 0, v5
	v_add_f32_e32 v5, 0x3727c5ac, v5
	v_rsq_f32_e32 v5, v5
	s_waitcnt vmcnt(4)
	v_lshlrev_b32_e32 v12, 16, v20
	v_and_b32_e32 v13, 0xffff0000, v20
	v_lshlrev_b32_e32 v14, 16, v21
	v_and_b32_e32 v15, 0xffff0000, v21
	v_lshlrev_b32_e32 v16, 16, v22
	v_and_b32_e32 v17, 0xffff0000, v22
	v_lshlrev_b32_e32 v18, 16, v23
	v_and_b32_e32 v19, 0xffff0000, v23
	v_fmac_f32_e32 v12, 0xbb000000, v4
	v_fmac_f32_e32 v13, 0xbb000000, v4
	v_fmac_f32_e32 v14, 0xbb000000, v4
	v_fmac_f32_e32 v15, 0xbb000000, v4
	v_fmac_f32_e32 v16, 0xbb000000, v4
	v_fmac_f32_e32 v17, 0xbb000000, v4
	v_fmac_f32_e32 v18, 0xbb000000, v4
	v_fmac_f32_e32 v19, 0xbb000000, v4
	v_mul_f32_e32 v4, v12, v5
	s_waitcnt vmcnt(2)
	v_fma_f32 v4, v28, v4, v24
	v_mul_f32_e32 v6, v13, v5
	v_cvt_pk_bf16_f32 v4, v4, v61
	v_mul_f32_e32 v7, v14, v5
	v_fma_f32 v6, v29, v6, v25
	ds_write_b16 v98, v4
	v_cvt_pk_bf16_f32 v4, v6, v61
	v_mul_f32_e32 v8, v15, v5
	v_fma_f32 v7, v30, v7, v26
	ds_write_b16 v98, v4 offset:272
	v_cvt_pk_bf16_f32 v4, v7, v61
	v_mul_f32_e32 v9, v16, v5
	v_fmac_f32_e32 v27, v31, v8
	ds_write_b16 v98, v4 offset:544
	v_cvt_pk_bf16_f32 v4, v27, v61
	v_mul_f32_e32 v10, v17, v5
	s_waitcnt vmcnt(0)
; #define LAS __attribute__((address_space(3)))
; __device__ __forceinline__ unsigned cvt_pk_bf16(float lo, float hi) { unsigned r; asm volatile("v_cvt_pk_bf16_f32 %0, %1, %2" : "=v"(r) : "v"(lo), "v"(hi)); return r; }
; __device__ __forceinline__ float bf_lo(unsigned w) { return __uint_as_float(w << 16); }
; __device__ __forceinline__ float bf_hi(unsigned w) { return __uint_as_float(w & 0xffff0000u); }
; __device__ __forceinline__ void phase_sgu(const Params& p, int l, LAS unsigned char* lds, const bf16_t* proj, const float* sgst, const bf16_t* sgw, bf16_t* ymix, int G, int wv) {
;     ...
;         for (int i = 0; i < 4; ++i) { const int c = tid + 512 * i, s = c >> 4, dc = c & 15; const size_t tok = tok0 + s;
;             const f32x4* sp = (const f32x4*)(sgst + tok * 16); const f32x4 q0 = sp[0], q1 = sp[1], q2 = sp[2], q3 = sp[3];
;             const float s1 = (q0[0] + q0[2]) + (q1[0] + q1[2]) + (q2[0] + q2[2]) + (q3[0] + q3[2]), s2 = (q0[1] + q0[3]) + (q1[1] + q1[3]) + (q2[1] + q2[3]) + (q3[1] + q3[3]);
;             const float mean = s1 * (1.f / 512.f), var = s2 * (1.f / 512.f) - mean * mean, rstd = __builtin_amdgcn_rsqf(fmaxf(var, 0.f) + EPS);
;             const u32x4 x = *(const u32x4*)(proj + tok * NIN + PJ_V + head * 128 + dc * 8);
;             const float xv[8] = {bf_lo(x.x), bf_hi(x.x), bf_lo(x.y), bf_hi(x.y), bf_lo(x.z), bf_hi(x.z), bf_lo(x.w), bf_hi(x.w)};
;             const f32x4 g0 = *(const f32x4*)(ng + head * 128 + dc * 8), g1 = *(const f32x4*)(ng + head * 128 + dc * 8 + 4);
;             const f32x4 b0 = *(const f32x4*)(nb_ + head * 128 + dc * 8), b1 = *(const f32x4*)(nb_ + head * 128 + dc * 8 + 4);
; #pragma unroll
;             for (int j = 0; j < 8; ++j) { const float gj = j < 4 ? g0[j & 3] : g1[j & 3], bj = j < 4 ? b0[j & 3] : b1[j & 3];
;                 const float v = (xv[j] - mean) * rstd * gj + bj;
;                 *(LAS bf16_t*)(lds + (dc * 8 + j) * SG_ROW + s * 2) = (bf16_t)(cvt_pk_bf16(v, 0.f) & 0xffffu); } }
;         const int tb = wave & 3, dh = wave >> 2;
;         const bf16_t* wrow = sgw + ((size_t)((l * 4 + head) * 128) + tb * 32 + l32) * 128 + 8 * hi;
;         bf16x8 af[8];
; #pragma unroll
;         for (int ks = 0; ks < 8; ++ks) { af[ks] = (bf16x8){0, 0, 0, 0, 0, 0, 0, 0}; if (ks < 2 * tb + 2) af[ks] = *(const bf16x8*)(wrow + 16 * ks); }
	v_fma_f32 v8, v32, v9, v36
	ds_write_b16 v98, v4 offset:816
	v_cvt_pk_bf16_f32 v4, v8, v61
	v_mul_f32_e32 v11, v18, v5
	v_fma_f32 v9, v33, v10, v37
	ds_write_b16 v98, v4 offset:1088
	v_cvt_pk_bf16_f32 v4, v9, v61
	v_mul_f32_e32 v5, v19, v5
	v_fma_f32 v10, v34, v11, v38
	ds_write_b16 v98, v4 offset:1360
	v_cvt_pk_bf16_f32 v4, v10, v61
	v_fmac_f32_e32 v39, v35, v5
	ds_write_b16 v98, v4 offset:1632
	v_cvt_pk_bf16_f32 v44, v39, v61
	global_load_dwordx4 v[4:7], v[40:41], off offset:16
	global_load_dwordx4 v[8:11], v[40:41], off
	global_load_dwordx4 v[12:15], v[40:41], off offset:48
	global_load_dwordx4 v[16:19], v[40:41], off offset:32
	v_lshl_add_u64 v[20:21], v[42:43], 0, v[72:73]
	v_add_co_u32_e32 v20, vcc, s45, v20
	s_waitcnt vmcnt(3)
	v_add_f32_e32 v5, v5, v7
	v_addc_co_u32_e32 v21, vcc, 0, v21, vcc
	global_load_dwordx4 v[20:23], v[20:21], off offset:3072
	s_nop 0
	global_load_dwordx4 v[24:27], v[2:3], off offset:2048
	global_load_dwordx4 v[28:31], v[0:1], off offset:2048
	global_load_dwordx4 v[32:35], v[0:1], off offset:2064
	global_load_dwordx4 v[36:39], v[2:3], off offset:2064
	s_waitcnt vmcnt(7)
	v_add_f32_e32 v2, v8, v10
	v_add_f32_e32 v3, v4, v6
	s_waitcnt vmcnt(5)
	v_add_f32_e32 v4, v16, v18
	v_add_f32_e32 v2, v2, v3
	v_add_f32_e32 v6, v12, v14
	v_add_f32_e32 v8, v9, v11
	v_add_f32_e32 v2, v2, v4
	v_add_f32_e32 v7, v17, v19
	v_add_f32_e32 v3, v8, v5
	v_add_f32_e32 v2, v2, v6
	v_add_f32_e32 v9, v13, v15
	v_add_f32_e32 v3, v3, v7
	v_mul_f32_e32 v4, 0x3b000000, v2
	v_add_f32_e32 v3, v3, v9
	v_mul_f32_e32 v4, v4, v4
	v_fma_f32 v3, v3, s43, -v4
	v_max_f32_e32 v3, 0, v3
	v_add_f32_e32 v3, 0x3727c5ac, v3
	v_rsq_f32_e32 v3, v3
	ds_write_b16 v98, v44 offset:1904
	v_or_b32_e32 v0, s66, v90
	v_lshlrev_b32_e32 v60, 8, v0
	v_lshl_add_u64 v[0:1], v[66:67], 0, v[60:61]
	s_and_b64 vcc, exec, s[6:7]
	s_waitcnt vmcnt(4)
	v_lshlrev_b32_e32 v10, 16, v20
	v_and_b32_e32 v11, 0xffff0000, v20
	v_lshlrev_b32_e32 v12, 16, v21
	v_and_b32_e32 v13, 0xffff0000, v21
	v_lshlrev_b32_e32 v14, 16, v22
	v_and_b32_e32 v15, 0xffff0000, v22
	v_lshlrev_b32_e32 v16, 16, v23
	v_and_b32_e32 v17, 0xffff0000, v23
	v_fmac_f32_e32 v10, 0xbb000000, v2
	v_fmac_f32_e32 v11, 0xbb000000, v2
	v_fmac_f32_e32 v12, 0xbb000000, v2
	v_fmac_f32_e32 v13, 0xbb000000, v2
	v_fmac_f32_e32 v14, 0xbb000000, v2
	v_fmac_f32_e32 v15, 0xbb000000, v2
	v_fmac_f32_e32 v16, 0xbb000000, v2
	v_fmac_f32_e32 v17, 0xbb000000, v2
	v_mul_f32_e32 v2, v10, v3
	s_waitcnt vmcnt(2)
	v_fma_f32 v2, v28, v2, v24
	v_mul_f32_e32 v4, v11, v3
	v_cvt_pk_bf16_f32 v2, v2, v61
	v_mul_f32_e32 v5, v12, v3
	v_fma_f32 v4, v29, v4, v25
	ds_write_b16 v99, v2
	v_cvt_pk_bf16_f32 v2, v4, v61
	v_mul_f32_e32 v6, v13, v3
	v_fma_f32 v5, v30, v5, v26
	ds_write_b16 v99, v2 offset:272
	v_cvt_pk_bf16_f32 v2, v5, v61
	v_mul_f32_e32 v7, v14, v3
	v_fmac_f32_e32 v27, v31, v6
	ds_write_b16 v99, v2 offset:544
	v_cvt_pk_bf16_f32 v2, v27, v61
	v_mul_f32_e32 v8, v15, v3
	s_waitcnt vmcnt(0)
	v_fma_f32 v6, v32, v7, v36
	ds_write_b16 v99, v2 offset:816
	v_cvt_pk_bf16_f32 v2, v6, v61
	v_mul_f32_e32 v9, v16, v3
	v_fma_f32 v7, v33, v8, v37
	ds_write_b16 v99, v2 offset:1088
	v_cvt_pk_bf16_f32 v2, v7, v61
	v_mul_f32_e32 v3, v17, v3
	v_fma_f32 v8, v34, v9, v38
	ds_write_b16 v99, v2 offset:1360
	v_cvt_pk_bf16_f32 v2, v8, v61
	v_fmac_f32_e32 v39, v35, v3
	ds_write_b16 v99, v2 offset:1632
	v_cvt_pk_bf16_f32 v2, v39, v61
	global_load_dwordx4 v[16:19], v[0:1], off
	global_load_dwordx4 v[40:43], v[0:1], off offset:32
	ds_write_b16 v99, v2 offset:1904
	s_cbranch_vccnz .LBB0_965
	global_load_dwordx4 v[32:35], v[0:1], off offset:64
	s_and_b64 vcc, exec, s[6:7]
	s_cbranch_vccnz .LBB0_966
